# barrier moved to first consumer (7.2): in the up GEMM the leading half's ALIGN barrier is executed just before the epilogue's halo-exchange barrier instead of at the epilogue top, so its rstd scaling
# baseline (speedup 1.0000x reference)
.LBB0_390:
	s_add_u32 s38, s42, 0x100
	s_addc_u32 s39, s43, 0
	s_add_i32 s4, 0, 0x10000
	s_cmp_eq_u32 s73, 12
	s_cselect_b32 s69, s29, s39
	s_cselect_b32 s68, vcc_lo, s38
	s_cselect_b32 s67, s37, s72
	s_cselect_b32 s66, vcc_hi, s59
	s_add_i32 s6, 0, 0x14000
	v_add_u32_e32 v142, s4, v251
	v_add_u32_e32 v158, s6, v251
	ds_read_b128 v[130:133], v142
	ds_read_b128 v[134:137], v142 offset:1024
	ds_read_b128 v[138:141], v142 offset:2048
	ds_read_b128 v[142:145], v142 offset:3072
	ds_read_b128 v[146:149], v158
	ds_read_b128 v[150:153], v158 offset:1024
	ds_read_b128 v[154:157], v158 offset:2048
	ds_read_b128 v[158:161], v158 offset:3072
	v_lshl_add_u64 v[194:195], s[42:43], 0, v[228:229]
	s_add_i32 m0, s75, 0xc000
	ds_read_b128 v[162:165], v244
	ds_read_b128 v[166:169], v244 offset:1024
	ds_read_b128 v[170:173], v244 offset:2048
	ds_read_b128 v[174:177], v244 offset:3072
	ds_read_b128 v[178:181], v244 offset:4096
	ds_read_b128 v[182:185], v244 offset:5120
	ds_read_b128 v[186:189], v244 offset:6144
	ds_read_b128 v[190:193], v244 offset:7168
	global_load_lds_dwordx4 v[194:195], off
	v_lshl_add_u64 v[194:195], s[42:43], 0, v[230:231]
	s_add_i32 m0, s75, 0xe000
	s_nop 0
	global_load_lds_dwordx4 v[194:195], off
	s_waitcnt vmcnt(8)
	s_waitcnt lgkmcnt(0)
	s_barrier
	s_setprio 1
	s_waitcnt lgkmcnt(0)
	v_mfma_f32_16x16x32_bf16 v[114:117], v[130:133], v[162:165], v[114:117]
	v_mfma_f32_16x16x32_bf16 v[122:125], v[138:141], v[162:165], v[122:125]
	v_mfma_f32_16x16x32_bf16 v[118:121], v[130:133], v[170:173], v[118:121]
	v_mfma_f32_16x16x32_bf16 v[126:129], v[138:141], v[170:173], v[126:129]
	v_mfma_f32_16x16x32_bf16 v[54:57], v[130:133], v[178:181], v[54:57]
	v_mfma_f32_16x16x32_bf16 v[70:73], v[138:141], v[178:181], v[70:73]
	v_mfma_f32_16x16x32_bf16 v[50:53], v[130:133], v[186:189], v[50:53]
	v_mfma_f32_16x16x32_bf16 v[66:69], v[138:141], v[186:189], v[66:69]
	v_mfma_f32_16x16x32_bf16 v[114:117], v[134:137], v[166:169], v[114:117]
	v_mfma_f32_16x16x32_bf16 v[122:125], v[142:145], v[166:169], v[122:125]
	v_mfma_f32_16x16x32_bf16 v[118:121], v[134:137], v[174:177], v[118:121]
	v_mfma_f32_16x16x32_bf16 v[126:129], v[142:145], v[174:177], v[126:129]
	v_mfma_f32_16x16x32_bf16 v[54:57], v[134:137], v[182:185], v[54:57]
	v_mfma_f32_16x16x32_bf16 v[70:73], v[142:145], v[182:185], v[70:73]
	v_mfma_f32_16x16x32_bf16 v[50:53], v[134:137], v[190:193], v[50:53]
	v_mfma_f32_16x16x32_bf16 v[66:69], v[142:145], v[190:193], v[66:69]
	s_setprio 0
	s_setprio 1
	v_mfma_f32_16x16x32_bf16 v[106:109], v[146:149], v[162:165], v[106:109]
	v_mfma_f32_16x16x32_bf16 v[42:45], v[154:157], v[162:165], v[42:45]
	v_mfma_f32_16x16x32_bf16 v[110:113], v[146:149], v[170:173], v[110:113]
	v_mfma_f32_16x16x32_bf16 v[46:49], v[154:157], v[170:173], v[46:49]
	v_mfma_f32_16x16x32_bf16 v[30:33], v[146:149], v[178:181], v[30:33]
	v_mfma_f32_16x16x32_bf16 v[14:17], v[154:157], v[178:181], v[14:17]
	v_mfma_f32_16x16x32_bf16 v[26:29], v[146:149], v[186:189], v[26:29]
	v_mfma_f32_16x16x32_bf16 v[10:13], v[154:157], v[186:189], v[10:13]
	v_mfma_f32_16x16x32_bf16 v[106:109], v[150:153], v[166:169], v[106:109]
	v_mfma_f32_16x16x32_bf16 v[42:45], v[158:161], v[166:169], v[42:45]
	v_mfma_f32_16x16x32_bf16 v[110:113], v[150:153], v[174:177], v[110:113]
	v_mfma_f32_16x16x32_bf16 v[46:49], v[158:161], v[174:177], v[46:49]
	v_mfma_f32_16x16x32_bf16 v[30:33], v[150:153], v[182:185], v[30:33]
	v_mfma_f32_16x16x32_bf16 v[14:17], v[158:161], v[182:185], v[14:17]
	v_mfma_f32_16x16x32_bf16 v[26:29], v[150:153], v[190:193], v[26:29]
	s_barrier
	v_mfma_f32_16x16x32_bf16 v[10:13], v[158:161], v[190:193], v[10:13]
	s_setprio 0
	s_add_i32 s4, s4, s74
	v_lshl_add_u64 v[194:195], s[66:67], 0, v[0:1]
	s_mov_b32 m0, s4
	ds_read_b128 v[162:165], v244 offset:16384
	ds_read_b128 v[166:169], v244 offset:17408
	ds_read_b128 v[170:173], v244 offset:18432
	ds_read_b128 v[174:177], v244 offset:19456
	ds_read_b128 v[178:181], v244 offset:20480
	ds_read_b128 v[182:185], v244 offset:21504
	ds_read_b128 v[186:189], v244 offset:22528
	ds_read_b128 v[190:193], v244 offset:23552
	global_load_lds_dwordx4 v[194:195], off
	s_add_i32 m0, s4, 0x2000
	s_add_u32 s4, s66, 0x40000
	v_lshl_add_u64 v[196:197], s[66:67], 0, v[224:225]
	s_addc_u32 s5, s67, 0
	s_add_i32 s6, s6, s74
	global_load_lds_dwordx4 v[196:197], off
	v_lshl_add_u64 v[198:199], s[4:5], 0, v[0:1]
	s_mov_b32 m0, s6
	v_lshl_add_u64 v[200:201], s[68:69], 0, v[222:223]
	global_load_lds_dwordx4 v[198:199], off
	v_lshl_add_u64 v[198:199], s[4:5], 0, v[224:225]
	s_add_i32 m0, s6, 0x2000
	s_nop 0
	global_load_lds_dwordx4 v[198:199], off
	v_lshl_add_u64 v[198:199], s[68:69], 0, v[226:227]
	s_mov_b32 m0, s75
	s_nop 0
	global_load_lds_dwordx4 v[198:199], off
	s_mov_b32 m0, s76
	s_nop 0
	global_load_lds_dwordx4 v[200:201], off
	s_waitcnt vmcnt(8)
	s_waitcnt lgkmcnt(0)
	s_barrier
	s_setprio 1
	s_waitcnt lgkmcnt(0)
	v_mfma_f32_16x16x32_bf16 v[38:41], v[130:133], v[162:165], v[38:41]
	v_mfma_f32_16x16x32_bf16 v[62:65], v[138:141], v[162:165], v[62:65]
	v_mfma_f32_16x16x32_bf16 v[34:37], v[130:133], v[170:173], v[34:37]
	v_mfma_f32_16x16x32_bf16 v[58:61], v[138:141], v[170:173], v[58:61]
	v_mfma_f32_16x16x32_bf16 v[102:105], v[130:133], v[178:181], v[102:105]
	v_mfma_f32_16x16x32_bf16 v[98:101], v[138:141], v[178:181], v[98:101]
	v_mfma_f32_16x16x32_bf16 v[94:97], v[130:133], v[186:189], v[94:97]
	v_mfma_f32_16x16x32_bf16 v[90:93], v[138:141], v[186:189], v[90:93]
	v_mfma_f32_16x16x32_bf16 v[38:41], v[134:137], v[166:169], v[38:41]
	v_mfma_f32_16x16x32_bf16 v[62:65], v[142:145], v[166:169], v[62:65]
	v_mfma_f32_16x16x32_bf16 v[34:37], v[134:137], v[174:177], v[34:37]
	v_mfma_f32_16x16x32_bf16 v[58:61], v[142:145], v[174:177], v[58:61]
	v_mfma_f32_16x16x32_bf16 v[102:105], v[134:137], v[182:185], v[102:105]
	v_mfma_f32_16x16x32_bf16 v[98:101], v[142:145], v[182:185], v[98:101]
	v_mfma_f32_16x16x32_bf16 v[94:97], v[134:137], v[190:193], v[94:97]
	v_mfma_f32_16x16x32_bf16 v[90:93], v[142:145], v[190:193], v[90:93]
	s_setprio 0
	s_setprio 1
	v_mfma_f32_16x16x32_bf16 v[22:25], v[146:149], v[162:165], v[22:25]
	v_mfma_f32_16x16x32_bf16 v[6:9], v[154:157], v[162:165], v[6:9]
	v_mfma_f32_16x16x32_bf16 v[18:21], v[146:149], v[170:173], v[18:21]
	v_mfma_f32_16x16x32_bf16 v[2:5], v[154:157], v[170:173], v[2:5]
	v_mfma_f32_16x16x32_bf16 v[86:89], v[146:149], v[178:181], v[86:89]
	v_mfma_f32_16x16x32_bf16 v[82:85], v[154:157], v[178:181], v[82:85]
	v_mfma_f32_16x16x32_bf16 v[78:81], v[146:149], v[186:189], v[78:81]
	v_mfma_f32_16x16x32_bf16 v[74:77], v[154:157], v[186:189], v[74:77]
	v_mfma_f32_16x16x32_bf16 v[22:25], v[150:153], v[166:169], v[22:25]
	v_mfma_f32_16x16x32_bf16 v[6:9], v[158:161], v[166:169], v[6:9]
	v_mfma_f32_16x16x32_bf16 v[18:21], v[150:153], v[174:177], v[18:21]
	v_mfma_f32_16x16x32_bf16 v[2:5], v[158:161], v[174:177], v[2:5]
	v_mfma_f32_16x16x32_bf16 v[86:89], v[150:153], v[182:185], v[86:89]
	v_mfma_f32_16x16x32_bf16 v[82:85], v[158:161], v[182:185], v[82:85]
	v_mfma_f32_16x16x32_bf16 v[78:81], v[150:153], v[190:193], v[78:81]
	s_barrier
	v_mfma_f32_16x16x32_bf16 v[74:77], v[158:161], v[190:193], v[74:77]
	s_setprio 0
	s_add_i32 s6, 0, 0x18000
	s_add_i32 s7, 0, 0x1c000
	v_add_u32_e32 v142, s6, v251
	v_add_u32_e32 v158, s7, v251
	ds_read_b128 v[130:133], v142
	ds_read_b128 v[134:137], v142 offset:1024
	ds_read_b128 v[138:141], v142 offset:2048
	ds_read_b128 v[142:145], v142 offset:3072
	ds_read_b128 v[146:149], v158
	ds_read_b128 v[150:153], v158 offset:1024
	ds_read_b128 v[154:157], v158 offset:2048
	ds_read_b128 v[158:161], v158 offset:3072
	s_add_u32 s4, s68, 0x2000
	s_addc_u32 s5, s69, 0
	s_mov_b32 m0, s77
	v_lshl_add_u64 v[202:203], s[4:5], 0, v[226:227]
	ds_read_b128 v[162:165], v244 offset:32768
	ds_read_b128 v[166:169], v244 offset:33792
	ds_read_b128 v[170:173], v244 offset:34816
	ds_read_b128 v[174:177], v244 offset:35840
	ds_read_b128 v[178:181], v244 offset:36864
	ds_read_b128 v[182:185], v244 offset:37888
	ds_read_b128 v[186:189], v244 offset:38912
	ds_read_b128 v[190:193], v244 offset:39936
	global_load_lds_dwordx4 v[202:203], off
	v_lshl_add_u64 v[202:203], s[4:5], 0, v[222:223]
	s_mov_b32 m0, s78
	s_nop 0
	global_load_lds_dwordx4 v[202:203], off
	s_waitcnt vmcnt(8)
	s_waitcnt lgkmcnt(0)
	s_barrier
	s_setprio 1
	s_waitcnt lgkmcnt(0)
	v_mfma_f32_16x16x32_bf16 v[114:117], v[130:133], v[162:165], v[114:117]
	v_mfma_f32_16x16x32_bf16 v[122:125], v[138:141], v[162:165], v[122:125]
	v_mfma_f32_16x16x32_bf16 v[118:121], v[130:133], v[170:173], v[118:121]
	v_mfma_f32_16x16x32_bf16 v[126:129], v[138:141], v[170:173], v[126:129]
	v_mfma_f32_16x16x32_bf16 v[54:57], v[130:133], v[178:181], v[54:57]
	v_mfma_f32_16x16x32_bf16 v[70:73], v[138:141], v[178:181], v[70:73]
	v_mfma_f32_16x16x32_bf16 v[50:53], v[130:133], v[186:189], v[50:53]
	v_mfma_f32_16x16x32_bf16 v[66:69], v[138:141], v[186:189], v[66:69]
	v_mfma_f32_16x16x32_bf16 v[114:117], v[134:137], v[166:169], v[114:117]
	v_mfma_f32_16x16x32_bf16 v[122:125], v[142:145], v[166:169], v[122:125]
	v_mfma_f32_16x16x32_bf16 v[118:121], v[134:137], v[174:177], v[118:121]
	v_mfma_f32_16x16x32_bf16 v[126:129], v[142:145], v[174:177], v[126:129]
	v_mfma_f32_16x16x32_bf16 v[54:57], v[134:137], v[182:185], v[54:57]
	v_mfma_f32_16x16x32_bf16 v[70:73], v[142:145], v[182:185], v[70:73]
	v_mfma_f32_16x16x32_bf16 v[50:53], v[134:137], v[190:193], v[50:53]
	v_mfma_f32_16x16x32_bf16 v[66:69], v[142:145], v[190:193], v[66:69]
	s_setprio 0
	s_setprio 1
	v_mfma_f32_16x16x32_bf16 v[106:109], v[146:149], v[162:165], v[106:109]
	v_mfma_f32_16x16x32_bf16 v[42:45], v[154:157], v[162:165], v[42:45]
	v_mfma_f32_16x16x32_bf16 v[110:113], v[146:149], v[170:173], v[110:113]
	v_mfma_f32_16x16x32_bf16 v[46:49], v[154:157], v[170:173], v[46:49]
	v_mfma_f32_16x16x32_bf16 v[30:33], v[146:149], v[178:181], v[30:33]
	v_mfma_f32_16x16x32_bf16 v[14:17], v[154:157], v[178:181], v[14:17]
	v_mfma_f32_16x16x32_bf16 v[26:29], v[146:149], v[186:189], v[26:29]
	v_mfma_f32_16x16x32_bf16 v[10:13], v[154:157], v[186:189], v[10:13]
	v_mfma_f32_16x16x32_bf16 v[106:109], v[150:153], v[166:169], v[106:109]
	v_mfma_f32_16x16x32_bf16 v[42:45], v[158:161], v[166:169], v[42:45]
	v_mfma_f32_16x16x32_bf16 v[110:113], v[150:153], v[174:177], v[110:113]
	v_mfma_f32_16x16x32_bf16 v[46:49], v[158:161], v[174:177], v[46:49]
	v_mfma_f32_16x16x32_bf16 v[30:33], v[150:153], v[182:185], v[30:33]
	v_mfma_f32_16x16x32_bf16 v[14:17], v[158:161], v[182:185], v[14:17]
	v_mfma_f32_16x16x32_bf16 v[26:29], v[150:153], v[190:193], v[26:29]
	s_barrier
	v_mfma_f32_16x16x32_bf16 v[10:13], v[158:161], v[190:193], v[10:13]
	s_setprio 0
	s_add_i32 s4, s6, s74
	v_lshl_add_u64 v[194:195], v[194:195], 0, s[82:83]
	s_mov_b32 m0, s4
	ds_read_b128 v[162:165], v244 offset:49152
	ds_read_b128 v[166:169], v244 offset:50176
	ds_read_b128 v[170:173], v244 offset:51200
	ds_read_b128 v[174:177], v244 offset:52224
	ds_read_b128 v[178:181], v244 offset:53248
	ds_read_b128 v[182:185], v244 offset:54272
	ds_read_b128 v[186:189], v244 offset:55296
	ds_read_b128 v[190:193], v244 offset:56320
	global_load_lds_dwordx4 v[194:195], off
	s_add_i32 m0, s4, 0x2000
	s_add_u32 s4, s66, 0x40080
	v_lshl_add_u64 v[194:195], v[196:197], 0, s[82:83]
	s_addc_u32 s5, s67, 0
	s_add_i32 s6, s7, s74
	global_load_lds_dwordx4 v[194:195], off
	v_lshl_add_u64 v[194:195], s[4:5], 0, v[0:1]
	s_mov_b32 m0, s6
	s_nop 0
	global_load_lds_dwordx4 v[194:195], off
	v_lshl_add_u64 v[194:195], s[4:5], 0, v[224:225]
	s_add_i32 m0, s6, 0x2000
	s_nop 0
	global_load_lds_dwordx4 v[194:195], off
	v_lshl_add_u64 v[194:195], v[198:199], 0, s[82:83]
	s_mov_b32 m0, s94
	s_nop 0
	global_load_lds_dwordx4 v[194:195], off
	v_lshl_add_u64 v[194:195], v[200:201], 0, s[82:83]
	s_mov_b32 m0, s95
	s_nop 0
	global_load_lds_dwordx4 v[194:195], off
	s_waitcnt vmcnt(8)
	s_waitcnt lgkmcnt(0)
	s_barrier
	s_setprio 1
	s_waitcnt lgkmcnt(0)
	v_mfma_f32_16x16x32_bf16 v[38:41], v[130:133], v[162:165], v[38:41]
	v_mfma_f32_16x16x32_bf16 v[62:65], v[138:141], v[162:165], v[62:65]
	v_mfma_f32_16x16x32_bf16 v[34:37], v[130:133], v[170:173], v[34:37]
	v_mfma_f32_16x16x32_bf16 v[58:61], v[138:141], v[170:173], v[58:61]
	v_mfma_f32_16x16x32_bf16 v[102:105], v[130:133], v[178:181], v[102:105]
	v_mfma_f32_16x16x32_bf16 v[98:101], v[138:141], v[178:181], v[98:101]
	v_mfma_f32_16x16x32_bf16 v[94:97], v[130:133], v[186:189], v[94:97]
	v_mfma_f32_16x16x32_bf16 v[90:93], v[138:141], v[186:189], v[90:93]
	v_mfma_f32_16x16x32_bf16 v[38:41], v[134:137], v[166:169], v[38:41]
	v_mfma_f32_16x16x32_bf16 v[62:65], v[142:145], v[166:169], v[62:65]
	v_mfma_f32_16x16x32_bf16 v[34:37], v[134:137], v[174:177], v[34:37]
	v_mfma_f32_16x16x32_bf16 v[58:61], v[142:145], v[174:177], v[58:61]
	v_mfma_f32_16x16x32_bf16 v[102:105], v[134:137], v[182:185], v[102:105]
	v_mfma_f32_16x16x32_bf16 v[98:101], v[142:145], v[182:185], v[98:101]
	v_mfma_f32_16x16x32_bf16 v[94:97], v[134:137], v[190:193], v[94:97]
	v_mfma_f32_16x16x32_bf16 v[90:93], v[142:145], v[190:193], v[90:93]
	s_setprio 0
	s_setprio 1
	v_mfma_f32_16x16x32_bf16 v[22:25], v[146:149], v[162:165], v[22:25]
	v_mfma_f32_16x16x32_bf16 v[6:9], v[154:157], v[162:165], v[6:9]
	v_mfma_f32_16x16x32_bf16 v[18:21], v[146:149], v[170:173], v[18:21]
	v_mfma_f32_16x16x32_bf16 v[2:5], v[154:157], v[170:173], v[2:5]
	v_mfma_f32_16x16x32_bf16 v[86:89], v[146:149], v[178:181], v[86:89]
	v_mfma_f32_16x16x32_bf16 v[82:85], v[154:157], v[178:181], v[82:85]
	v_mfma_f32_16x16x32_bf16 v[78:81], v[146:149], v[186:189], v[78:81]
	v_mfma_f32_16x16x32_bf16 v[74:77], v[154:157], v[186:189], v[74:77]
	v_mfma_f32_16x16x32_bf16 v[22:25], v[150:153], v[166:169], v[22:25]
	v_mfma_f32_16x16x32_bf16 v[6:9], v[158:161], v[166:169], v[6:9]
	v_mfma_f32_16x16x32_bf16 v[18:21], v[150:153], v[174:177], v[18:21]
	v_mfma_f32_16x16x32_bf16 v[2:5], v[158:161], v[174:177], v[2:5]
	v_mfma_f32_16x16x32_bf16 v[86:89], v[150:153], v[182:185], v[86:89]
	v_mfma_f32_16x16x32_bf16 v[82:85], v[158:161], v[182:185], v[82:85]
	v_mfma_f32_16x16x32_bf16 v[78:81], v[150:153], v[190:193], v[78:81]
	s_barrier
	v_mfma_f32_16x16x32_bf16 v[74:77], v[158:161], v[190:193], v[74:77]
	s_setprio 0
	s_add_i32 s73, s73, 2
	s_add_u32 s59, s59, 0x100
	s_addc_u32 s72, s72, 0
	s_cmp_gt_u32 s73, 13
	s_mov_b64 s[42:43], s[38:39]
	s_cbranch_scc0 .LBB0_390
	s_and_b64 vcc, exec, s[50:51]
	s_cbranch_vccz .LBB0_393
.LBB0_393:
	s_lshl_b32 s4, s27, 8
	v_mov_b32_e32 v167, v250
	v_mov_b32_e32 v166, v249
	s_add_i32 s4, s4, s96
	s_nop 0
	v_lshl_add_u32 v232, v166, 3, s4
	v_lshl_add_u32 v202, v250, 3, s89
	v_lshlrev_b32_e32 v202, 2, v202
	s_lshl_b32 s100, s26, 9
	s_add_u32 s100, s48, s100
	s_addc_u32 s101, s49, 0
	global_load_dwordx4 v[158:161], v202, s[100:101]
	global_load_dwordx4 v[190:193], v202, s[100:101] offset:16
	s_add_u32 s100, s100, 0x5000
	s_addc_u32 s101, s101, 0
	global_load_dwordx4 v[162:165], v202, s[100:101] offset:2048
	global_load_dwordx4 v[194:197], v202, s[100:101] offset:2064
	s_add_u32 s100, s100, 0x3000
	s_addc_u32 s101, s101, 0
	global_load_dwordx4 v[146:149], v202, s[100:101] offset:1024
	s_add_u32 s100, s100, 0x3000
	s_addc_u32 s101, s101, 0
	global_load_dwordx4 v[174:177], v202, s[100:101]
	global_load_dwordx4 v[198:201], v202, s[100:101] offset:16
	s_add_u32 s100, s100, 0x2000
	s_addc_u32 s101, s101, 0
	global_load_dwordx4 v[150:153], v202, s[100:101] offset:3072
	s_add_i32 s4, s58, -1
	s_lshl_b32 s4, s4, 10
	s_add_i32 s4, s4, 0x21000
	v_lshrrev_b32_e32 v136, 8, v248
	v_lshlrev_b32_e32 v136, 9, v136
	v_lshl_add_u32 v136, v249, 5, v136
	v_add_u32_e32 v136, s4, v136
	ds_read_b32 v134, v136
	ds_read_b32 v135, v136 offset:4
	ds_read_b32 v240, v136 offset:8
	ds_read_b32 v242, v136 offset:12
	ds_read_b32 v236, v136 offset:16
	ds_read_b32 v238, v136 offset:20
	ds_read_b32 v130, v136 offset:24
	ds_read_b32 v131, v136 offset:28
	s_waitcnt lgkmcnt(0)
	v_lshl_add_u32 v138, v167, 3, s89
	v_ashrrev_i32_e32 v139, 31, v138
	s_waitcnt lgkmcnt(0)
	s_waitcnt lgkmcnt(0)
	s_nop 0
	s_nop 0
	s_nop 0
	s_nop 0
	v_pk_mul_f32 v[116:117], v[116:117], v[134:135] op_sel_hi:[1,0]
	v_pk_mul_f32 v[114:115], v[114:115], v[134:135] op_sel_hi:[1,0]
	v_pk_mul_f32 v[124:125], v[124:125], v[134:135] op_sel_hi:[1,0]
	v_pk_mul_f32 v[122:123], v[122:123], v[134:135] op_sel_hi:[1,0]
	v_pk_mul_f32 v[108:109], v[108:109], v[134:135] op_sel_hi:[1,0]
	v_pk_mul_f32 v[106:107], v[106:107], v[134:135] op_sel_hi:[1,0]
	v_pk_mul_f32 v[44:45], v[44:45], v[134:135] op_sel_hi:[1,0]
	v_pk_mul_f32 v[42:43], v[42:43], v[134:135] op_sel_hi:[1,0]
	s_nop 0
	v_mov_b32_e32 v134, v135
	v_pk_mul_f32 v[120:121], v[120:121], v[134:135] op_sel_hi:[1,0]
	v_pk_mul_f32 v[118:119], v[118:119], v[134:135] op_sel_hi:[1,0]
	v_pk_mul_f32 v[128:129], v[128:129], v[134:135] op_sel_hi:[1,0]
	v_pk_mul_f32 v[126:127], v[126:127], v[134:135] op_sel_hi:[1,0]
	v_pk_mul_f32 v[112:113], v[112:113], v[134:135] op_sel_hi:[1,0]
	v_pk_mul_f32 v[110:111], v[110:111], v[134:135] op_sel_hi:[1,0]
	v_pk_mul_f32 v[48:49], v[48:49], v[134:135] op_sel_hi:[1,0]
	v_pk_mul_f32 v[46:47], v[46:47], v[134:135] op_sel_hi:[1,0]
	s_nop 0
	s_nop 0
	s_nop 0
	s_waitcnt lgkmcnt(0)
	s_waitcnt lgkmcnt(2)
	v_or_b32_e32 v134, s71, v166
	v_cmp_eq_u32_e32 vcc, 0, v134
	s_waitcnt lgkmcnt(0)
	s_and_saveexec_b64 s[38:39], vcc
	s_cbranch_execz .LBB0_395
	s_lshl_b32 s4, s26, 8
	s_ashr_i32 s5, s4, 31
	s_mul_i32 s7, s27, 0x16000
	s_mul_hi_i32 s6, s27, 0x16000
	s_add_u32 s7, s84, s7
	s_addc_u32 s6, s88, s6
	s_lshl_b64 s[4:5], s[4:5], 2
	s_add_u32 s4, s7, s4
	s_addc_u32 s5, s6, s5
	v_lshl_add_u64 v[134:135], v[138:139], 2, s[4:5]
	s_mov_b64 s[4:5], 0x5800
	global_store_dwordx4 v[134:135], v[114:117], off
	global_store_dwordx4 v[134:135], v[122:125], off offset:16
	global_store_dwordx4 v[134:135], v[106:109], off offset:512
	global_store_dwordx4 v[134:135], v[42:45], off offset:528
	v_lshl_add_u64 v[136:137], v[134:135], 0, s[4:5]
	v_add_co_u32_e32 v134, vcc, 0x5000, v134
	s_nop 1
	v_addc_co_u32_e32 v135, vcc, 0, v135, vcc
	global_store_dwordx4 v[134:135], v[118:121], off offset:2048
	global_store_dwordx4 v[136:137], v[126:129], off offset:16
	global_store_dwordx4 v[136:137], v[110:113], off offset:512
	global_store_dwordx4 v[136:137], v[46:49], off offset:528

.LBB0_400:
	s_mov_b32 s100, 0xbfb8aa3b
	s_or_b64 exec, exec, s[38:39]
	s_and_b64 vcc, exec, s[50:51]
	s_cbranch_vccz .Lalign_late
	s_barrier
.Lalign_late:
	s_ashr_i32 s27, s26, 31
	s_lshl_b64 s[4:5], s[26:27], 7
	v_lshl_add_u64 v[234:235], s[4:5], 0, v[138:139]
	v_lshl_add_u64 v[86:87], v[234:235], 2, s[48:49]
	s_waitcnt lgkmcnt(0)
	s_barrier
	v_mov_b32_dpp v90, v135 row_shr:1 row_mask:0xf bank_mask:0xf bound_ctrl:1
	v_add_co_u32_e32 v80, vcc, s80, v86
	v_mov_b32_dpp v91, v144 row_shr:1 row_mask:0xf bank_mask:0xf bound_ctrl:1
	s_nop 0
	v_addc_co_u32_e32 v81, vcc, 0, v87, vcc
	v_add_co_u32_e32 v88, vcc, s64, v86
	global_load_dwordx4 v[138:141], v[80:81], off offset:3072
	v_addc_co_u32_e32 v89, vcc, 0, v87, vcc
	v_mov_b32_dpp v80, v134 row_shr:1 row_mask:0xf bank_mask:0xf bound_ctrl:1
	v_lshlrev_b32_e32 v78, 7, v167
	v_mov_b32_dpp v79, v142 row_shr:1 row_mask:0xf bank_mask:0xf bound_ctrl:1
	v_mov_b32_dpp v81, v143 row_shr:1 row_mask:0xf bank_mask:0xf bound_ctrl:1
	v_mov_b32_dpp v92, v136 row_shr:1 row_mask:0xf bank_mask:0xf bound_ctrl:1
	v_mov_b32_dpp v93, v145 row_shr:1 row_mask:0xf bank_mask:0xf bound_ctrl:1
	v_mov_b32_dpp v94, v137 row_shr:1 row_mask:0xf bank_mask:0xf bound_ctrl:1
	v_cmp_ne_u32_e64 s[42:43], 0, v166
	s_nor_b64 s[26:27], s[52:53], s[42:43]
	v_add_u32_e32 v233, s97, v78
	v_cndmask_b32_e64 v185, 0, v93, s[42:43]
	v_cndmask_b32_e64 v184, 0, v91, s[42:43]
	v_cndmask_b32_e64 v183, 0, v81, s[42:43]
	v_cndmask_b32_e64 v182, 0, v79, s[42:43]
	v_cndmask_b32_e64 v189, 0, v94, s[42:43]
	v_cndmask_b32_e64 v188, 0, v92, s[42:43]
	v_cndmask_b32_e64 v187, 0, v90, s[42:43]
	v_cndmask_b32_e64 v186, 0, v80, s[42:43]
	s_and_saveexec_b64 s[38:39], s[26:27]
	s_cbranch_execz .LBB0_402
	ds_read_b128 v[186:189], v233
	ds_read_b128 v[182:185], v233 offset:64
